# P6/P9 residual epilogues: raised priority for one wave of each SIMD pair
# baseline (speedup 1.0000x reference)
.LBB0_486:
	s_setprio 0
	v_readlane_b32 s4, v254, 15
	v_readlane_b32 s5, v254, 16
	s_andn2_b64 vcc, exec, s[4:5]
	s_cbranch_vccnz .LBB0_962
	v_readlane_b32 s4, v254, 13
	v_readlane_b32 s6, v254, 2
	v_readlane_b32 s7, v254, 3
	v_readlane_b32 s5, v254, 14
	s_mov_b32 s0, s6
	s_mov_b32 s3, s7
	s_mov_b32 s6, s7
	s_cmpk_gt_i32 s6, 0x69f
	s_mov_b32 s9, -1
	s_cbranch_scc1 .LBB0_489
	s_ashr_i32 s7, s6, 31
	s_lshr_b32 s7, s7, 29
	s_add_i32 s7, s6, s7
	s_ashr_i32 s9, s7, 3
	s_and_b32 s7, s7, -8
	s_sub_i32 s6, s6, s7
	s_lshr_b32 s7, s6, 31
	s_or_b32 s7, s7, 0xd4
	s_mul_i32 s6, s7, s6
	s_add_i32 s6, s6, s9
	s_mul_hi_i32 s7, s6, 0x4d4873ed
	s_lshr_b32 s9, s7, 31
	s_ashr_i32 s7, s7, 7
	s_add_i32 s7, s7, s9
	s_lshl_b32 s9, s7, 3
	s_sub_i32 s10, 32, s9
	s_min_u32 s10, s10, 8
	s_mulk_i32 s7, 0x1a8
	s_sub_i32 s11, s6, s7
	v_cvt_f32_ubyte0_e32 v3, s10
	v_cvt_f32_i32_e32 v2, s11
	s_waitcnt lgkmcnt(0)
	v_rcp_iflag_f32_e32 v4, v3
	s_ashr_i32 s6, s11, 30
	s_or_b32 s12, s6, 1
	v_mul_f32_e32 v4, v2, v4
	v_trunc_f32_e32 v4, v4
	v_fma_f32 v2, -v4, v3, v2
	v_cvt_i32_f32_e32 v4, v4
	v_cmp_ge_f32_e64 s[6:7], |v2|, v3
	s_and_b64 s[6:7], s[6:7], exec
	s_cselect_b32 s6, s12, 0
	v_readfirstlane_b32 s7, v4
	s_add_i32 s6, s7, s6
	s_mul_i32 s6, s6, s10
	s_sub_i32 s6, s11, s6
	s_sext_i32_i16 s6, s6
	s_add_i32 s9, s9, s6

.LBB0_2351:
	s_cmpk_gt_u32 s0, 0xff
	s_cbranch_scc1 .Lp6prio_skip
	s_setprio 2

.LBB0_2445:
	s_setprio 0
	v_readlane_b32 s4, v255, 29
	v_readlane_b32 s5, v255, 30
	s_andn2_b64 vcc, exec, s[4:5]
	s_cbranch_vccnz .LBB0_2920
	v_readlane_b32 s4, v254, 13
	v_readlane_b32 s6, v254, 2
	v_readlane_b32 s7, v254, 3
	v_readlane_b32 s5, v254, 14
	s_mov_b32 s0, s6
	s_mov_b32 s3, s7
	s_mov_b32 s6, s7
	s_cmpk_gt_i32 s6, 0x57f
	s_mov_b32 s9, -1
	s_cbranch_scc1 .LBB0_2448
	s_ashr_i32 s7, s6, 31
	s_lshr_b32 s7, s7, 29
	s_add_i32 s7, s6, s7
	s_ashr_i32 s9, s7, 3
	s_and_b32 s7, s7, -8
	s_sub_i32 s6, s6, s7
	s_lshr_b32 s7, s6, 31
	s_or_b32 s7, s7, 0xb0
	s_mul_i32 s6, s7, s6
	s_add_i32 s6, s6, s9
	s_mul_hi_i32 s7, s6, 0x2e8ba2e9
	s_lshr_b32 s9, s7, 31
	s_ashr_i32 s7, s7, 6
	s_add_i32 s7, s7, s9
	s_lshl_b32 s9, s7, 3
	s_waitcnt lgkmcnt(0)
	s_sub_i32 s10, 32, s9
	s_min_u32 s10, s10, 8
	s_mulk_i32 s7, 0x160
	s_sub_i32 s11, s6, s7
	v_cvt_f32_ubyte0_e32 v3, s10
	v_cvt_f32_i32_e32 v2, s11
	v_rcp_iflag_f32_e32 v4, v3
	s_ashr_i32 s6, s11, 30
	s_or_b32 s12, s6, 1
	v_mul_f32_e32 v4, v2, v4
	v_trunc_f32_e32 v4, v4
	v_fma_f32 v2, -v4, v3, v2
	v_cvt_i32_f32_e32 v4, v4
	v_cmp_ge_f32_e64 s[6:7], |v2|, v3
	s_and_b64 s[6:7], s[6:7], exec
	s_cselect_b32 s6, s12, 0
	v_readfirstlane_b32 s7, v4
	s_add_i32 s6, s7, s6
	s_mul_i32 s6, s6, s10
	s_sub_i32 s6, s11, s6
	s_sext_i32_i16 s6, s6
	s_add_i32 s9, s9, s6
